# P0 weight transposition: the 16 LDS read-backs per item issued together (were 16 serialized ds_read2 round trips), on top of v36
# baseline (speedup 1.0000x reference)
; #define LAS __attribute__((address_space(3)))
; __device__ __forceinline__ unsigned pk2(float lo, float hi) { return pg8::cvt_pk_bf16(lo, hi); }
; __device__ __forceinline__ void transpose_item(const float* W, int ldw, int nvalid, int K, bf16* WT, int k0, int n0, int drow0, LAS float* scr, int lane) {
;     const int r8 = lane >> 3, c4 = lane & 7;
; #pragma unroll
;     for (int i = 0; i < 8; ++i) { const int kk = 8 * i + r8; const int n = n0 + 4 * c4;
;         f32x4 v = {0.f, 0.f, 0.f, 0.f};
;         if (n < nvalid) v = *(const f32x4*)(W + (size_t)(k0 + kk) * ldw + n);
;         LAS float* d = scr + kk * 33 + 4 * c4; d[0] = v.x; d[1] = v.y; d[2] = v.z; d[3] = v.w; }
;     asm volatile("s_waitcnt lgkmcnt(0)" ::: "memory");
;     const int c = lane & 7;
; #pragma unroll
;     for (int j = 0; j < 4; ++j) { const int n = (lane >> 3) + 8 * j; const LAS float* s = scr + (8 * c) * 33 + n;
;         u32x4 o; o.x = pk2(s[0 * 33], s[1 * 33]); o.y = pk2(s[2 * 33], s[3 * 33]); o.z = pk2(s[4 * 33], s[5 * 33]); o.w = pk2(s[6 * 33], s[7 * 33]);
;         *(u32x4*)(WT + (size_t)(drow0 + n) * K + k0 + 8 * c) = o; }
;     asm volatile("s_waitcnt lgkmcnt(0)" ::: "memory");
; }
; __device__ __forceinline__ void transpose_plain(const float* W, int K, int N, int Npad, bf16* WT, int item, LAS float* scr, int lane) {
;     const int nblk = Npad / 32, kb = item / nblk, nb = item % nblk;
;     transpose_item(W, N, N, K, WT, 64 * kb, 32 * nb, 32 * nb, scr, lane);
.LBB0_10:
	s_cmpk_gt_i32 s39, 0x47f
	s_mov_b64 s[0:1], -1
	s_cbranch_scc0 .LBB0_58
	s_cmpk_gt_u32 s39, 0x4bf
	s_cbranch_scc0 .LBB0_53
	s_cmpk_gt_u32 s39, 0x5cbf
	s_cbranch_scc0 .LBB0_50
	s_cmpk_gt_u32 s39, 0x88bf
	s_cbranch_scc0 .LBB0_47
	s_cmpk_gt_u32 s39, 0x93bf
	s_cbranch_scc0 .LBB0_36
	s_cmpk_gt_u32 s39, 0x97bf
	s_cbranch_scc0 .LBB0_33
	s_cmpk_gt_u32 s39, 0x9bbf
	s_cbranch_scc0 .LBB0_30
	s_cmpk_gt_u32 s39, 0xa1bf
	s_cbranch_scc0 .LBB0_27
	s_cmpk_gt_u32 s39, 0xa7bf
	s_cbranch_scc0 .LBB0_24
	s_lshl_b32 s0, s39, 5
	s_and_b32 s10, s0, 0x3e0
	s_lshl_b32 s14, s39, 1
	v_or_b32_e32 v2, s10, v65
	v_or_b32_e32 v3, s10, v1
	v_or_b32_e32 v4, s10, v67
	v_or_b32_e32 v5, s10, v69
	v_or_b32_e32 v7, s10, v71
	s_cmpk_gt_u32 s39, 0xa9bf
	s_mov_b64 s[0:1], -1
	v_lshlrev_b32_e32 v32, 2, v2
	v_lshlrev_b32_e32 v8, 11, v3
	v_lshlrev_b32_e32 v6, 11, v4
	v_lshlrev_b32_e32 v4, 11, v5
	v_lshlrev_b32_e32 v2, 11, v7
	s_cbranch_scc0 .LBB0_21
	s_add_i32 s0, s14, 0xac80
	s_and_b32 s0, s0, 0x1ffc0
	v_or_b32_e32 v3, s0, v1
	v_lshlrev_b32_e32 v10, 12, v3
	v_or_b32_e32 v3, s0, v67
	v_lshlrev_b32_e32 v12, 12, v3
	v_or_b32_e32 v3, s0, v69
	v_lshlrev_b32_e32 v18, 12, v3
	v_or_b32_e32 v3, s0, v71
	v_lshlrev_b32_e32 v20, 12, v3
	v_or_b32_e32 v3, s0, v73
	v_lshlrev_b32_e32 v26, 12, v3
	v_or_b32_e32 v3, s0, v75
	v_lshl_add_u64 v[60:61], s[62:63], 0, v[32:33]
	v_mov_b32_e32 v11, v33
	v_mov_b32_e32 v13, v33
	v_mov_b32_e32 v19, v33
	v_mov_b32_e32 v21, v33
	v_mov_b32_e32 v27, v33
	v_lshlrev_b32_e32 v28, 12, v3
	v_mov_b32_e32 v29, v33
	v_lshl_add_u64 v[10:11], v[60:61], 0, v[10:11]
	v_lshl_add_u64 v[14:15], v[60:61], 0, v[12:13]
	v_lshl_add_u64 v[18:19], v[60:61], 0, v[18:19]
	v_lshl_add_u64 v[22:23], v[60:61], 0, v[20:21]
	v_lshl_add_u64 v[26:27], v[60:61], 0, v[26:27]
	v_lshl_add_u64 v[52:53], v[60:61], 0, v[28:29]
	global_load_dwordx4 v[10:13], v[10:11], off
	s_nop 0
	global_load_dwordx4 v[14:17], v[14:15], off
	s_nop 0
	global_load_dwordx4 v[18:21], v[18:19], off
	s_nop 0
	global_load_dwordx4 v[22:25], v[22:23], off
	s_nop 0
	global_load_dwordx4 v[26:29], v[26:27], off
	s_nop 0
	global_load_dwordx4 v[52:55], v[52:53], off
	v_or_b32_e32 v3, s0, v77
	v_lshlrev_b32_e32 v56, 12, v3
	v_mov_b32_e32 v57, v33
	v_lshl_add_u64 v[56:57], v[60:61], 0, v[56:57]
	v_or_b32_e32 v3, s0, v79
	global_load_dwordx4 v[56:59], v[56:57], off
	v_lshlrev_b32_e32 v62, 12, v3
	v_mov_b32_e32 v63, v33
	v_lshl_add_u64 v[60:61], v[60:61], 0, v[62:63]
	global_load_dwordx4 v[60:63], v[60:61], off
	s_lshl_b32 s10, s0, 1
	v_mov_b32_e32 v9, v33
	v_mov_b32_e32 v7, v33
	v_mov_b32_e32 v5, v33
	v_mov_b32_e32 v3, v33
	s_mov_b64 s[0:1], 0
	s_waitcnt vmcnt(7)
	ds_write2_b32 v31, v10, v11 offset1:1
	ds_write2_b32 v31, v12, v13 offset0:2 offset1:3
	s_waitcnt vmcnt(6)
	ds_write2_b32 v87, v14, v15 offset1:1
	ds_write2_b32 v88, v16, v17 offset1:1
	s_waitcnt vmcnt(5)
	ds_write2_b32 v89, v18, v19 offset1:1
	ds_write2_b32 v90, v20, v21 offset1:1
	s_waitcnt vmcnt(4)
	ds_write2_b32 v91, v22, v23 offset1:1
	ds_write2_b32 v92, v24, v25 offset1:1
	s_waitcnt vmcnt(3)
	ds_write2_b32 v93, v26, v27 offset1:1
	ds_write2_b32 v94, v28, v29 offset1:1
	s_waitcnt vmcnt(2)
	ds_write2_b32 v95, v52, v53 offset1:1
	ds_write2_b32 v96, v54, v55 offset1:1
	s_waitcnt vmcnt(1)
	ds_write2_b32 v97, v56, v57 offset1:1
	ds_write2_b32 v98, v58, v59 offset1:1
	s_waitcnt vmcnt(0)
	ds_write2_b32 v99, v60, v61 offset1:1
	ds_write2_b32 v100, v62, v63 offset1:1
	s_waitcnt lgkmcnt(0)
	ds_read2_b32 v[148:149], v81 offset1:33
	ds_read2_b32 v[150:151], v81 offset0:66 offset1:99
	ds_read2_b32 v[152:153], v81 offset0:132 offset1:165
	ds_read2_b32 v[154:155], v81 offset0:198 offset1:231
	ds_read2_b32 v[156:157], v81 offset0:8 offset1:41
	ds_read2_b32 v[158:159], v81 offset0:74 offset1:107
	ds_read2_b32 v[160:161], v81 offset0:140 offset1:173
	ds_read2_b32 v[162:163], v81 offset0:206 offset1:239
	ds_read2_b32 v[164:165], v81 offset0:16 offset1:49
	ds_read2_b32 v[166:167], v81 offset0:82 offset1:115
	ds_read2_b32 v[168:169], v81 offset0:148 offset1:181
	ds_read2_b32 v[170:171], v81 offset0:214 offset1:247
	ds_read2_b32 v[172:173], v81 offset0:24 offset1:57
	ds_read2_b32 v[174:175], v81 offset0:90 offset1:123
	ds_read2_b32 v[176:177], v81 offset0:156 offset1:189
	ds_read2_b32 v[178:179], v81 offset0:222 offset1:255
	s_waitcnt lgkmcnt(0)
	v_cvt_pk_bf16_f32 v180, v148, v149
	v_cvt_pk_bf16_f32 v181, v150, v151
	v_lshl_add_u64 v[16:17], v[36:37], 0, s[10:11]
	v_cvt_pk_bf16_f32 v182, v152, v153
	v_cvt_pk_bf16_f32 v183, v154, v155
	v_lshl_add_u64 v[18:19], v[16:17], 0, v[8:9]
	global_store_dwordx4 v[18:19], v[180:183], off
	v_lshl_add_u64 v[18:19], v[16:17], 0, v[6:7]
	v_cvt_pk_bf16_f32 v184, v156, v157
	v_cvt_pk_bf16_f32 v185, v158, v159
	v_cvt_pk_bf16_f32 v186, v160, v161
	v_cvt_pk_bf16_f32 v187, v162, v163
	global_store_dwordx4 v[18:19], v[184:187], off
	v_lshl_add_u64 v[18:19], v[16:17], 0, v[4:5]
	v_cvt_pk_bf16_f32 v188, v164, v165
	v_cvt_pk_bf16_f32 v189, v166, v167
	v_cvt_pk_bf16_f32 v190, v168, v169
	v_cvt_pk_bf16_f32 v191, v170, v171
	global_store_dwordx4 v[18:19], v[188:191], off
	s_nop 0
	v_cvt_pk_bf16_f32 v192, v172, v173
	v_cvt_pk_bf16_f32 v193, v174, v175
	v_cvt_pk_bf16_f32 v194, v176, v177
	v_cvt_pk_bf16_f32 v195, v178, v179
	v_lshl_add_u64 v[14:15], v[16:17], 0, v[2:3]
	global_store_dwordx4 v[14:15], v[192:195], off
	s_waitcnt lgkmcnt(0)
; #define LAS __attribute__((address_space(3)))
; __device__ __forceinline__ unsigned pk2(float lo, float hi) { return pg8::cvt_pk_bf16(lo, hi); }
; __device__ __forceinline__ void transpose_item(const float* W, int ldw, int nvalid, int K, bf16* WT, int k0, int n0, int drow0, LAS float* scr, int lane) {
;     const int r8 = lane >> 3, c4 = lane & 7;
; #pragma unroll
;     for (int i = 0; i < 8; ++i) { const int kk = 8 * i + r8; const int n = n0 + 4 * c4;
;         f32x4 v = {0.f, 0.f, 0.f, 0.f};
;         if (n < nvalid) v = *(const f32x4*)(W + (size_t)(k0 + kk) * ldw + n);
;         LAS float* d = scr + kk * 33 + 4 * c4; d[0] = v.x; d[1] = v.y; d[2] = v.z; d[3] = v.w; }
;     asm volatile("s_waitcnt lgkmcnt(0)" ::: "memory");
;     const int c = lane & 7;
; #pragma unroll
;     for (int j = 0; j < 4; ++j) { const int n = (lane >> 3) + 8 * j; const LAS float* s = scr + (8 * c) * 33 + n;
;         u32x4 o; o.x = pk2(s[0 * 33], s[1 * 33]); o.y = pk2(s[2 * 33], s[3 * 33]); o.z = pk2(s[4 * 33], s[5 * 33]); o.w = pk2(s[6 * 33], s[7 * 33]);
;         *(u32x4*)(WT + (size_t)(drow0 + n) * K + k0 + 8 * c) = o; }
;     asm volatile("s_waitcnt lgkmcnt(0)" ::: "memory");
; }
; __device__ __forceinline__ void transpose_plain(const float* W, int K, int N, int Npad, bf16* WT, int item, LAS float* scr, int lane) {
;     const int nblk = Npad / 32, kb = item / nblk, nb = item % nblk;
;     transpose_item(W, N, N, K, WT, 64 * kb, 32 * nb, 32 * nb, scr, lane);
.LBB0_21:
	s_andn2_b64 vcc, exec, s[0:1]
	s_cbranch_vccnz .LBB0_23
	s_add_i32 s14, s14, 0xb080
	s_and_b32 s0, s14, 0x1ffc0
	v_readlane_b32 s40, v252, 16
	v_readlane_b32 s50, v252, 26
	v_readlane_b32 s51, v252, 27
	v_or_b32_e32 v3, s0, v1
	s_lshl_b32 s10, s0, 1
	v_lshl_add_u64 v[60:61], s[50:51], 0, v[32:33]
	v_lshlrev_b32_e32 v32, 12, v3
	v_or_b32_e32 v3, s0, v67
	v_lshl_add_u64 v[10:11], v[60:61], 0, v[32:33]
	v_lshlrev_b32_e32 v32, 12, v3
	v_or_b32_e32 v3, s0, v69
	v_lshl_add_u64 v[14:15], v[60:61], 0, v[32:33]
	v_lshlrev_b32_e32 v32, 12, v3
	v_or_b32_e32 v3, s0, v71
	v_lshl_add_u64 v[18:19], v[60:61], 0, v[32:33]
	v_lshlrev_b32_e32 v32, 12, v3
	v_or_b32_e32 v3, s0, v73
	v_lshl_add_u64 v[22:23], v[60:61], 0, v[32:33]
	v_lshlrev_b32_e32 v32, 12, v3
	v_or_b32_e32 v3, s0, v75
	v_lshl_add_u64 v[26:27], v[60:61], 0, v[32:33]
	v_lshlrev_b32_e32 v32, 12, v3
	v_lshl_add_u64 v[52:53], v[60:61], 0, v[32:33]
	global_load_dwordx4 v[10:13], v[10:11], off
	s_nop 0
	global_load_dwordx4 v[14:17], v[14:15], off
	s_nop 0
	global_load_dwordx4 v[18:21], v[18:19], off
	s_nop 0
	global_load_dwordx4 v[22:25], v[22:23], off
	s_nop 0
	global_load_dwordx4 v[26:29], v[26:27], off
	s_nop 0
	global_load_dwordx4 v[52:55], v[52:53], off
	v_or_b32_e32 v3, s0, v77
	v_lshlrev_b32_e32 v32, 12, v3
	v_lshl_add_u64 v[56:57], v[60:61], 0, v[32:33]
	v_or_b32_e32 v3, s0, v79
	global_load_dwordx4 v[56:59], v[56:57], off
	v_lshlrev_b32_e32 v32, 12, v3
	v_lshl_add_u64 v[60:61], v[60:61], 0, v[32:33]
	global_load_dwordx4 v[60:63], v[60:61], off
	v_mov_b32_e32 v9, v33
	v_mov_b32_e32 v7, v33
	v_mov_b32_e32 v5, v33
	v_mov_b32_e32 v3, v33
	v_readlane_b32 s41, v252, 17
	v_readlane_b32 s42, v252, 18
	v_readlane_b32 s43, v252, 19
	v_readlane_b32 s44, v252, 20
	v_readlane_b32 s45, v252, 21
	v_readlane_b32 s46, v252, 22
	v_readlane_b32 s47, v252, 23
	v_readlane_b32 s48, v252, 24
	v_readlane_b32 s49, v252, 25
	v_readlane_b32 s52, v252, 28
	v_readlane_b32 s53, v252, 29
	v_readlane_b32 s54, v252, 30
	v_readlane_b32 s55, v252, 31
	s_waitcnt vmcnt(7)
	ds_write2_b32 v31, v10, v11 offset1:1
	ds_write2_b32 v31, v12, v13 offset0:2 offset1:3
	s_waitcnt vmcnt(6)
	ds_write2_b32 v87, v14, v15 offset1:1
	ds_write2_b32 v88, v16, v17 offset1:1
	s_waitcnt vmcnt(5)
	ds_write2_b32 v89, v18, v19 offset1:1
	ds_write2_b32 v90, v20, v21 offset1:1
	s_waitcnt vmcnt(4)
	ds_write2_b32 v91, v22, v23 offset1:1
	ds_write2_b32 v92, v24, v25 offset1:1
	s_waitcnt vmcnt(3)
	ds_write2_b32 v93, v26, v27 offset1:1
	ds_write2_b32 v94, v28, v29 offset1:1
	s_waitcnt vmcnt(2)
	ds_write2_b32 v95, v52, v53 offset1:1
	ds_write2_b32 v96, v54, v55 offset1:1
	s_waitcnt vmcnt(1)
	ds_write2_b32 v97, v56, v57 offset1:1
	ds_write2_b32 v98, v58, v59 offset1:1
	s_waitcnt vmcnt(0)
	ds_write2_b32 v99, v60, v61 offset1:1
	ds_write2_b32 v100, v62, v63 offset1:1
	s_waitcnt lgkmcnt(0)
	ds_read2_b32 v[148:149], v81 offset1:33
	ds_read2_b32 v[150:151], v81 offset0:66 offset1:99
	ds_read2_b32 v[152:153], v81 offset0:132 offset1:165
	ds_read2_b32 v[154:155], v81 offset0:198 offset1:231
	ds_read2_b32 v[156:157], v81 offset0:8 offset1:41
	ds_read2_b32 v[158:159], v81 offset0:74 offset1:107
	ds_read2_b32 v[160:161], v81 offset0:140 offset1:173
	ds_read2_b32 v[162:163], v81 offset0:206 offset1:239
	ds_read2_b32 v[164:165], v81 offset0:16 offset1:49
	ds_read2_b32 v[166:167], v81 offset0:82 offset1:115
	ds_read2_b32 v[168:169], v81 offset0:148 offset1:181
	ds_read2_b32 v[170:171], v81 offset0:214 offset1:247
	ds_read2_b32 v[172:173], v81 offset0:24 offset1:57
	ds_read2_b32 v[174:175], v81 offset0:90 offset1:123
	ds_read2_b32 v[176:177], v81 offset0:156 offset1:189
	ds_read2_b32 v[178:179], v81 offset0:222 offset1:255
	s_waitcnt lgkmcnt(0)
	v_cvt_pk_bf16_f32 v180, v148, v149
	v_cvt_pk_bf16_f32 v181, v150, v151
	v_lshl_add_u64 v[16:17], v[38:39], 0, s[10:11]
	v_cvt_pk_bf16_f32 v182, v152, v153
	v_lshl_add_u64 v[8:9], v[16:17], 0, v[8:9]
	v_cvt_pk_bf16_f32 v183, v154, v155
	global_store_dwordx4 v[8:9], v[180:183], off
	v_cvt_pk_bf16_f32 v184, v156, v157
	v_cvt_pk_bf16_f32 v185, v158, v159
	v_cvt_pk_bf16_f32 v186, v160, v161
	v_lshl_add_u64 v[6:7], v[16:17], 0, v[6:7]
	v_cvt_pk_bf16_f32 v187, v162, v163
	global_store_dwordx4 v[6:7], v[184:187], off
	v_cvt_pk_bf16_f32 v188, v164, v165
	v_cvt_pk_bf16_f32 v189, v166, v167
	v_cvt_pk_bf16_f32 v190, v168, v169
	v_lshl_add_u64 v[4:5], v[16:17], 0, v[4:5]
	v_cvt_pk_bf16_f32 v191, v170, v171
	global_store_dwordx4 v[4:5], v[188:191], off
	v_cvt_pk_bf16_f32 v192, v172, v173
	v_cvt_pk_bf16_f32 v193, v174, v175
	v_lshl_add_u64 v[2:3], v[16:17], 0, v[2:3]
	v_cvt_pk_bf16_f32 v194, v176, v177
	v_cvt_pk_bf16_f32 v195, v178, v179
	global_store_dwordx4 v[2:3], v[192:195], off
	s_waitcnt lgkmcnt(0)

; #define LAS __attribute__((address_space(3)))
; __device__ __forceinline__ unsigned pk2(float lo, float hi) { return pg8::cvt_pk_bf16(lo, hi); }
; __device__ __forceinline__ void transpose_item(const float* W, int ldw, int nvalid, int K, bf16* WT, int k0, int n0, int drow0, LAS float* scr, int lane) {
;     const int r8 = lane >> 3, c4 = lane & 7;
; #pragma unroll
;     for (int i = 0; i < 8; ++i) { const int kk = 8 * i + r8; const int n = n0 + 4 * c4;
;         f32x4 v = {0.f, 0.f, 0.f, 0.f};
;         if (n < nvalid) v = *(const f32x4*)(W + (size_t)(k0 + kk) * ldw + n);
;         LAS float* d = scr + kk * 33 + 4 * c4; d[0] = v.x; d[1] = v.y; d[2] = v.z; d[3] = v.w; }
;     asm volatile("s_waitcnt lgkmcnt(0)" ::: "memory");
;     const int c = lane & 7;
; #pragma unroll
;     for (int j = 0; j < 4; ++j) { const int n = (lane >> 3) + 8 * j; const LAS float* s = scr + (8 * c) * 33 + n;
;         u32x4 o; o.x = pk2(s[0 * 33], s[1 * 33]); o.y = pk2(s[2 * 33], s[3 * 33]); o.z = pk2(s[4 * 33], s[5 * 33]); o.w = pk2(s[6 * 33], s[7 * 33]);
;         *(u32x4*)(WT + (size_t)(drow0 + n) * K + k0 + 8 * c) = o; }
;     asm volatile("s_waitcnt lgkmcnt(0)" ::: "memory");
; }
; __device__ __forceinline__ void transpose_plain(const float* W, int K, int N, int Npad, bf16* WT, int item, LAS float* scr, int lane) {
;     const int nblk = Npad / 32, kb = item / nblk, nb = item % nblk;
;     transpose_item(W, N, N, K, WT, 64 * kb, 32 * nb, 32 * nb, scr, lane);
.LBB0_24:
	s_andn2_b64 vcc, exec, s[0:1]
	s_cbranch_vccnz .LBB0_26
	s_add_i32 s0, s39, 0x5e40
	s_and_b32 s1, s0, 0xffff
	s_mul_i32 s1, s1, 0xaaab
	s_lshr_b32 s10, s1, 16
	s_lshr_b32 s1, s1, 22
	s_mulk_i32 s1, 0x60
	s_sub_i32 s0, s0, s1
	s_lshl_b32 s0, s0, 5
	s_and_b32 s0, s0, 0xffe0
	s_and_b32 s1, s10, 0xffc0
	v_or_b32_e32 v2, s0, v65
	v_lshlrev_b32_e32 v32, 2, v2
	v_readlane_b32 s40, v252, 16
	v_or_b32_e32 v2, s1, v1
	v_readlane_b32 s52, v252, 28
	v_readlane_b32 s53, v252, 29
	v_mul_u32_u24_e32 v2, 0xc00, v2
	v_or_b32_e32 v4, s1, v67
	v_lshl_add_u64 v[52:53], s[52:53], 0, v[32:33]
	v_lshlrev_b32_e32 v32, 2, v2
	v_mul_u32_u24_e32 v4, 0xc00, v4
	v_or_b32_e32 v10, s1, v69
	v_lshl_add_u64 v[2:3], v[52:53], 0, v[32:33]
	v_lshlrev_b32_e32 v32, 2, v4
	v_mul_u32_u24_e32 v10, 0xc00, v10
	v_or_b32_e32 v12, s1, v71
	v_lshl_add_u64 v[6:7], v[52:53], 0, v[32:33]
	v_lshlrev_b32_e32 v32, 2, v10
	v_mul_u32_u24_e32 v12, 0xc00, v12
	v_or_b32_e32 v18, s1, v73
	v_lshl_add_u64 v[10:11], v[52:53], 0, v[32:33]
	v_lshlrev_b32_e32 v32, 2, v12
	v_mul_u32_u24_e32 v18, 0xc00, v18
	v_or_b32_e32 v20, s1, v75
	v_lshl_add_u64 v[14:15], v[52:53], 0, v[32:33]
	v_lshlrev_b32_e32 v32, 2, v18
	v_mul_u32_u24_e32 v20, 0xc00, v20
	v_lshl_add_u64 v[18:19], v[52:53], 0, v[32:33]
	v_lshlrev_b32_e32 v32, 2, v20
	v_lshl_add_u64 v[22:23], v[52:53], 0, v[32:33]
	global_load_dwordx4 v[2:5], v[2:3], off
	s_nop 0
	global_load_dwordx4 v[6:9], v[6:7], off
	s_nop 0
	global_load_dwordx4 v[10:13], v[10:11], off
	s_nop 0
	global_load_dwordx4 v[14:17], v[14:15], off
	s_nop 0
	global_load_dwordx4 v[18:21], v[18:19], off
	s_nop 0
	global_load_dwordx4 v[22:25], v[22:23], off
	v_or_b32_e32 v26, s1, v77
	v_mul_u32_u24_e32 v26, 0xc00, v26
	v_lshlrev_b32_e32 v32, 2, v26
	v_lshl_add_u64 v[26:27], v[52:53], 0, v[32:33]
	v_or_b32_e32 v32, s1, v79
	v_mul_u32_u24_e32 v32, 0xc00, v32
	global_load_dwordx4 v[26:29], v[26:27], off
	v_lshlrev_b32_e32 v32, 2, v32
	v_lshl_add_u64 v[52:53], v[52:53], 0, v[32:33]
	global_load_dwordx4 v[52:55], v[52:53], off
	s_lshl_b32 s10, s1, 1
	v_readlane_b32 s41, v252, 17
	v_readlane_b32 s42, v252, 18
	v_readlane_b32 s43, v252, 19
	v_readlane_b32 s44, v252, 20
	v_readlane_b32 s45, v252, 21
	v_readlane_b32 s46, v252, 22
	v_readlane_b32 s47, v252, 23
	v_readlane_b32 s48, v252, 24
	v_readlane_b32 s49, v252, 25
	v_readlane_b32 s50, v252, 26
	v_readlane_b32 s51, v252, 27
	v_readlane_b32 s54, v252, 30
	v_readlane_b32 s55, v252, 31
	s_waitcnt vmcnt(7)
	ds_write2_b32 v31, v2, v3 offset1:1
	ds_write2_b32 v31, v4, v5 offset0:2 offset1:3
	s_waitcnt vmcnt(6)
	ds_write2_b32 v87, v6, v7 offset1:1
	ds_write2_b32 v88, v8, v9 offset1:1
	s_waitcnt vmcnt(5)
	ds_write2_b32 v89, v10, v11 offset1:1
	ds_write2_b32 v90, v12, v13 offset1:1
	s_waitcnt vmcnt(4)
	ds_write2_b32 v91, v14, v15 offset1:1
	ds_write2_b32 v92, v16, v17 offset1:1
	s_waitcnt vmcnt(3)
	ds_write2_b32 v93, v18, v19 offset1:1
	ds_write2_b32 v94, v20, v21 offset1:1
	s_waitcnt vmcnt(2)
	ds_write2_b32 v95, v22, v23 offset1:1
	ds_write2_b32 v96, v24, v25 offset1:1
	s_waitcnt vmcnt(1)
	ds_write2_b32 v97, v26, v27 offset1:1
	ds_write2_b32 v98, v28, v29 offset1:1
	s_waitcnt vmcnt(0)
	ds_write2_b32 v99, v52, v53 offset1:1
	ds_write2_b32 v100, v54, v55 offset1:1
	s_waitcnt lgkmcnt(0)
	ds_read2_b32 v[148:149], v81 offset1:33
	ds_read2_b32 v[150:151], v81 offset0:66 offset1:99
	ds_read2_b32 v[152:153], v81 offset0:132 offset1:165
	ds_read2_b32 v[154:155], v81 offset0:198 offset1:231
	ds_read2_b32 v[156:157], v81 offset0:8 offset1:41
	ds_read2_b32 v[158:159], v81 offset0:74 offset1:107
	ds_read2_b32 v[160:161], v81 offset0:140 offset1:173
	ds_read2_b32 v[162:163], v81 offset0:206 offset1:239
	ds_read2_b32 v[164:165], v81 offset0:16 offset1:49
	ds_read2_b32 v[166:167], v81 offset0:82 offset1:115
	ds_read2_b32 v[168:169], v81 offset0:148 offset1:181
	ds_read2_b32 v[170:171], v81 offset0:214 offset1:247
	ds_read2_b32 v[172:173], v81 offset0:24 offset1:57
	ds_read2_b32 v[174:175], v81 offset0:90 offset1:123
	ds_read2_b32 v[176:177], v81 offset0:156 offset1:189
	ds_read2_b32 v[178:179], v81 offset0:222 offset1:255
	s_waitcnt lgkmcnt(0)
	v_cvt_pk_bf16_f32 v180, v148, v149
	v_or_b32_e32 v10, s0, v1
	v_cvt_pk_bf16_f32 v181, v150, v151
	v_lshl_add_u64 v[8:9], v[40:41], 0, s[10:11]
	v_lshlrev_b32_e32 v32, 11, v10
	v_cvt_pk_bf16_f32 v182, v152, v153
	v_cvt_pk_bf16_f32 v183, v154, v155
	v_lshl_add_u64 v[10:11], v[8:9], 0, v[32:33]
	global_store_dwordx4 v[10:11], v[180:183], off
	v_or_b32_e32 v10, s0, v67
	v_lshlrev_b32_e32 v32, 11, v10
	v_cvt_pk_bf16_f32 v184, v156, v157
	v_cvt_pk_bf16_f32 v185, v158, v159
	v_cvt_pk_bf16_f32 v186, v160, v161
	v_cvt_pk_bf16_f32 v187, v162, v163
	v_lshl_add_u64 v[10:11], v[8:9], 0, v[32:33]
	global_store_dwordx4 v[10:11], v[184:187], off
	v_or_b32_e32 v10, s0, v69
	v_lshlrev_b32_e32 v32, 11, v10
	v_cvt_pk_bf16_f32 v188, v164, v165
	v_cvt_pk_bf16_f32 v189, v166, v167
	v_cvt_pk_bf16_f32 v190, v168, v169
	v_cvt_pk_bf16_f32 v191, v170, v171
	v_lshl_add_u64 v[10:11], v[8:9], 0, v[32:33]
	global_store_dwordx4 v[10:11], v[188:191], off
	s_nop 0
	v_cvt_pk_bf16_f32 v192, v172, v173
	v_cvt_pk_bf16_f32 v193, v174, v175
	v_cvt_pk_bf16_f32 v194, v176, v177
	v_or_b32_e32 v5, s0, v71
	v_lshlrev_b32_e32 v32, 11, v5
	v_cvt_pk_bf16_f32 v195, v178, v179
	v_lshl_add_u64 v[6:7], v[8:9], 0, v[32:33]
	global_store_dwordx4 v[6:7], v[192:195], off
	s_waitcnt lgkmcnt(0)

; #define LAS __attribute__((address_space(3)))
; __device__ __forceinline__ unsigned pk2(float lo, float hi) { return pg8::cvt_pk_bf16(lo, hi); }
; __device__ __forceinline__ void transpose_item(const float* W, int ldw, int nvalid, int K, bf16* WT, int k0, int n0, int drow0, LAS float* scr, int lane) {
;     const int r8 = lane >> 3, c4 = lane & 7;
; #pragma unroll
;     for (int i = 0; i < 8; ++i) { const int kk = 8 * i + r8; const int n = n0 + 4 * c4;
;         f32x4 v = {0.f, 0.f, 0.f, 0.f};
;         if (n < nvalid) v = *(const f32x4*)(W + (size_t)(k0 + kk) * ldw + n);
;         LAS float* d = scr + kk * 33 + 4 * c4; d[0] = v.x; d[1] = v.y; d[2] = v.z; d[3] = v.w; }
;     asm volatile("s_waitcnt lgkmcnt(0)" ::: "memory");
;     const int c = lane & 7;
; #pragma unroll
;     for (int j = 0; j < 4; ++j) { const int n = (lane >> 3) + 8 * j; const LAS float* s = scr + (8 * c) * 33 + n;
;         u32x4 o; o.x = pk2(s[0 * 33], s[1 * 33]); o.y = pk2(s[2 * 33], s[3 * 33]); o.z = pk2(s[4 * 33], s[5 * 33]); o.w = pk2(s[6 * 33], s[7 * 33]);
;         *(u32x4*)(WT + (size_t)(drow0 + n) * K + k0 + 8 * c) = o; }
;     asm volatile("s_waitcnt lgkmcnt(0)" ::: "memory");
; }
; __device__ __forceinline__ void transpose_plain(const float* W, int K, int N, int Npad, bf16* WT, int item, LAS float* scr, int lane) {
;     const int nblk = Npad / 32, kb = item / nblk, nb = item % nblk;
;     transpose_item(W, N, N, K, WT, 64 * kb, 32 * nb, 32 * nb, scr, lane);
.LBB0_27:
	s_andn2_b64 vcc, exec, s[0:1]
	s_cbranch_vccnz .LBB0_29
	s_add_i32 s0, s39, 0x6440
	s_and_b32 s1, s0, 0xffff
	s_mul_i32 s1, s1, 0xaaab
	s_lshr_b32 s10, s1, 16
	s_lshr_b32 s1, s1, 22
	s_mulk_i32 s1, 0x60
	s_sub_i32 s0, s0, s1
	s_lshl_b32 s0, s0, 5
	s_and_b32 s0, s0, 0xffe0
	s_and_b32 s1, s10, 0xffc0
	v_or_b32_e32 v2, s0, v65
	v_lshlrev_b32_e32 v32, 2, v2
	v_readlane_b32 s40, v252, 16
	v_or_b32_e32 v2, s1, v1
	v_readlane_b32 s48, v252, 24
	v_readlane_b32 s49, v252, 25
	v_mul_u32_u24_e32 v2, 0xc00, v2
	v_or_b32_e32 v4, s1, v67
	v_lshl_add_u64 v[52:53], s[48:49], 0, v[32:33]
	v_lshlrev_b32_e32 v32, 2, v2
	v_mul_u32_u24_e32 v4, 0xc00, v4
	v_or_b32_e32 v10, s1, v69
	v_lshl_add_u64 v[2:3], v[52:53], 0, v[32:33]
	v_lshlrev_b32_e32 v32, 2, v4
	v_mul_u32_u24_e32 v10, 0xc00, v10
	v_or_b32_e32 v12, s1, v71
	v_lshl_add_u64 v[6:7], v[52:53], 0, v[32:33]
	v_lshlrev_b32_e32 v32, 2, v10
	v_mul_u32_u24_e32 v12, 0xc00, v12
	v_or_b32_e32 v18, s1, v73
	v_lshl_add_u64 v[10:11], v[52:53], 0, v[32:33]
	v_lshlrev_b32_e32 v32, 2, v12
	v_mul_u32_u24_e32 v18, 0xc00, v18
	v_or_b32_e32 v20, s1, v75
	v_lshl_add_u64 v[14:15], v[52:53], 0, v[32:33]
	v_lshlrev_b32_e32 v32, 2, v18
	v_mul_u32_u24_e32 v20, 0xc00, v20
	v_lshl_add_u64 v[18:19], v[52:53], 0, v[32:33]
	v_lshlrev_b32_e32 v32, 2, v20
	v_lshl_add_u64 v[22:23], v[52:53], 0, v[32:33]
	global_load_dwordx4 v[2:5], v[2:3], off
	s_nop 0
	global_load_dwordx4 v[6:9], v[6:7], off
	s_nop 0
	global_load_dwordx4 v[10:13], v[10:11], off
	s_nop 0
	global_load_dwordx4 v[14:17], v[14:15], off
	s_nop 0
	global_load_dwordx4 v[18:21], v[18:19], off
	s_nop 0
	global_load_dwordx4 v[22:25], v[22:23], off
	v_or_b32_e32 v26, s1, v77
	v_mul_u32_u24_e32 v26, 0xc00, v26
	v_lshlrev_b32_e32 v32, 2, v26
	v_lshl_add_u64 v[26:27], v[52:53], 0, v[32:33]
	v_or_b32_e32 v32, s1, v79
	v_mul_u32_u24_e32 v32, 0xc00, v32
	global_load_dwordx4 v[26:29], v[26:27], off
	v_lshlrev_b32_e32 v32, 2, v32
	v_lshl_add_u64 v[52:53], v[52:53], 0, v[32:33]
	global_load_dwordx4 v[52:55], v[52:53], off
	s_lshl_b32 s10, s1, 1
	v_readlane_b32 s41, v252, 17
	v_readlane_b32 s42, v252, 18
	v_readlane_b32 s43, v252, 19
	v_readlane_b32 s44, v252, 20
	v_readlane_b32 s45, v252, 21
	v_readlane_b32 s46, v252, 22
	v_readlane_b32 s47, v252, 23
	v_readlane_b32 s50, v252, 26
	v_readlane_b32 s51, v252, 27
	v_readlane_b32 s52, v252, 28
	v_readlane_b32 s53, v252, 29
	v_readlane_b32 s54, v252, 30
	v_readlane_b32 s55, v252, 31
	s_waitcnt vmcnt(7)
	ds_write2_b32 v31, v2, v3 offset1:1
	ds_write2_b32 v31, v4, v5 offset0:2 offset1:3
	s_waitcnt vmcnt(6)
	ds_write2_b32 v87, v6, v7 offset1:1
	ds_write2_b32 v88, v8, v9 offset1:1
	s_waitcnt vmcnt(5)
	ds_write2_b32 v89, v10, v11 offset1:1
	ds_write2_b32 v90, v12, v13 offset1:1
	s_waitcnt vmcnt(4)
	ds_write2_b32 v91, v14, v15 offset1:1
	ds_write2_b32 v92, v16, v17 offset1:1
	s_waitcnt vmcnt(3)
	ds_write2_b32 v93, v18, v19 offset1:1
	ds_write2_b32 v94, v20, v21 offset1:1
	s_waitcnt vmcnt(2)
	ds_write2_b32 v95, v22, v23 offset1:1
	ds_write2_b32 v96, v24, v25 offset1:1
	s_waitcnt vmcnt(1)
	ds_write2_b32 v97, v26, v27 offset1:1
	ds_write2_b32 v98, v28, v29 offset1:1
	s_waitcnt vmcnt(0)
	ds_write2_b32 v99, v52, v53 offset1:1
	ds_write2_b32 v100, v54, v55 offset1:1
	s_waitcnt lgkmcnt(0)
	ds_read2_b32 v[148:149], v81 offset1:33
	ds_read2_b32 v[150:151], v81 offset0:66 offset1:99
	ds_read2_b32 v[152:153], v81 offset0:132 offset1:165
	ds_read2_b32 v[154:155], v81 offset0:198 offset1:231
	ds_read2_b32 v[156:157], v81 offset0:8 offset1:41
	ds_read2_b32 v[158:159], v81 offset0:74 offset1:107
	ds_read2_b32 v[160:161], v81 offset0:140 offset1:173
	ds_read2_b32 v[162:163], v81 offset0:206 offset1:239
	ds_read2_b32 v[164:165], v81 offset0:16 offset1:49
	ds_read2_b32 v[166:167], v81 offset0:82 offset1:115
	ds_read2_b32 v[168:169], v81 offset0:148 offset1:181
	ds_read2_b32 v[170:171], v81 offset0:214 offset1:247
	ds_read2_b32 v[172:173], v81 offset0:24 offset1:57
	ds_read2_b32 v[174:175], v81 offset0:90 offset1:123
	ds_read2_b32 v[176:177], v81 offset0:156 offset1:189
	ds_read2_b32 v[178:179], v81 offset0:222 offset1:255
	s_waitcnt lgkmcnt(0)
	v_cvt_pk_bf16_f32 v180, v148, v149
	v_or_b32_e32 v10, s0, v1
	v_cvt_pk_bf16_f32 v181, v150, v151
	v_lshl_add_u64 v[8:9], v[42:43], 0, s[10:11]
	v_lshlrev_b32_e32 v32, 11, v10
	v_cvt_pk_bf16_f32 v182, v152, v153
	v_cvt_pk_bf16_f32 v183, v154, v155
	v_lshl_add_u64 v[10:11], v[8:9], 0, v[32:33]
	global_store_dwordx4 v[10:11], v[180:183], off
	v_or_b32_e32 v10, s0, v67
	v_lshlrev_b32_e32 v32, 11, v10
	v_cvt_pk_bf16_f32 v184, v156, v157
	v_cvt_pk_bf16_f32 v185, v158, v159
	v_cvt_pk_bf16_f32 v186, v160, v161
	v_cvt_pk_bf16_f32 v187, v162, v163
	v_lshl_add_u64 v[10:11], v[8:9], 0, v[32:33]
	global_store_dwordx4 v[10:11], v[184:187], off
	v_or_b32_e32 v10, s0, v69
	v_lshlrev_b32_e32 v32, 11, v10
	v_cvt_pk_bf16_f32 v188, v164, v165
	v_cvt_pk_bf16_f32 v189, v166, v167
	v_cvt_pk_bf16_f32 v190, v168, v169
	v_cvt_pk_bf16_f32 v191, v170, v171
	v_lshl_add_u64 v[10:11], v[8:9], 0, v[32:33]
	global_store_dwordx4 v[10:11], v[188:191], off
	s_nop 0
	v_cvt_pk_bf16_f32 v192, v172, v173
	v_cvt_pk_bf16_f32 v193, v174, v175
	v_cvt_pk_bf16_f32 v194, v176, v177
	v_or_b32_e32 v5, s0, v71
	v_lshlrev_b32_e32 v32, 11, v5
	v_cvt_pk_bf16_f32 v195, v178, v179
	v_lshl_add_u64 v[6:7], v[8:9], 0, v[32:33]
	global_store_dwordx4 v[6:7], v[192:195], off
	s_waitcnt lgkmcnt(0)

; #define LAS __attribute__((address_space(3)))
; __device__ __forceinline__ unsigned pk2(float lo, float hi) { return pg8::cvt_pk_bf16(lo, hi); }
; __device__ __forceinline__ void transpose_item(const float* W, int ldw, int nvalid, int K, bf16* WT, int k0, int n0, int drow0, LAS float* scr, int lane) {
;     const int r8 = lane >> 3, c4 = lane & 7;
; #pragma unroll
;     for (int i = 0; i < 8; ++i) { const int kk = 8 * i + r8; const int n = n0 + 4 * c4;
;         f32x4 v = {0.f, 0.f, 0.f, 0.f};
;         if (n < nvalid) v = *(const f32x4*)(W + (size_t)(k0 + kk) * ldw + n);
;         LAS float* d = scr + kk * 33 + 4 * c4; d[0] = v.x; d[1] = v.y; d[2] = v.z; d[3] = v.w; }
;     asm volatile("s_waitcnt lgkmcnt(0)" ::: "memory");
;     const int c = lane & 7;
; #pragma unroll
;     for (int j = 0; j < 4; ++j) { const int n = (lane >> 3) + 8 * j; const LAS float* s = scr + (8 * c) * 33 + n;
;         u32x4 o; o.x = pk2(s[0 * 33], s[1 * 33]); o.y = pk2(s[2 * 33], s[3 * 33]); o.z = pk2(s[4 * 33], s[5 * 33]); o.w = pk2(s[6 * 33], s[7 * 33]);
;         *(u32x4*)(WT + (size_t)(drow0 + n) * K + k0 + 8 * c) = o; }
;     asm volatile("s_waitcnt lgkmcnt(0)" ::: "memory");
; }
; __device__ __forceinline__ void transpose_plain(const float* W, int K, int N, int Npad, bf16* WT, int item, LAS float* scr, int lane) {
;     const int nblk = Npad / 32, kb = item / nblk, nb = item % nblk;
;     transpose_item(W, N, N, K, WT, 64 * kb, 32 * nb, 32 * nb, scr, lane);
.LBB0_30:
	s_andn2_b64 vcc, exec, s[0:1]
	s_cbranch_vccnz .LBB0_32
	s_add_i32 s16, s39, 0xffff6840
	s_lshr_b32 s10, s16, 8
	v_readlane_b32 s40, v252, 16
	s_lshl_b64 s[0:1], s[10:11], 21
	v_readlane_b32 s42, v252, 18
	v_readlane_b32 s43, v252, 19
	s_add_u32 s14, s42, s0
	s_addc_u32 s15, s43, s1
	s_lshl_b64 s[0:1], s[10:11], 20
	v_readlane_b32 s10, v252, 38
	s_add_u32 s10, s10, s0
	v_readlane_b32 s0, v252, 39
	s_addc_u32 s1, s0, s1
	s_lshl_b32 s0, s16, 3
	s_and_b32 s16, s0, 0x7c0
	s_lshl_b32 s0, s39, 5
	s_and_b32 s0, s0, 0xe0
	v_or_b32_e32 v2, s0, v65
	v_lshlrev_b32_e32 v32, 2, v2
	v_or_b32_e32 v2, s16, v1
	v_lshl_add_u64 v[52:53], s[14:15], 0, v[32:33]
	v_lshlrev_b32_e32 v32, 10, v2
	v_or_b32_e32 v4, s16, v67
	v_lshl_add_u64 v[2:3], v[52:53], 0, v[32:33]
	v_lshlrev_b32_e32 v32, 10, v4
	v_or_b32_e32 v10, s16, v69
	v_lshl_add_u64 v[6:7], v[52:53], 0, v[32:33]
	v_lshlrev_b32_e32 v32, 10, v10
	v_or_b32_e32 v12, s16, v71
	v_lshl_add_u64 v[10:11], v[52:53], 0, v[32:33]
	v_lshlrev_b32_e32 v32, 10, v12
	v_or_b32_e32 v18, s16, v73
	v_lshl_add_u64 v[14:15], v[52:53], 0, v[32:33]
	v_lshlrev_b32_e32 v32, 10, v18
	v_or_b32_e32 v20, s16, v75
	v_lshl_add_u64 v[18:19], v[52:53], 0, v[32:33]
	v_lshlrev_b32_e32 v32, 10, v20
	v_lshl_add_u64 v[22:23], v[52:53], 0, v[32:33]
	global_load_dwordx4 v[2:5], v[2:3], off
	s_nop 0
	global_load_dwordx4 v[6:9], v[6:7], off
	s_nop 0
	global_load_dwordx4 v[10:13], v[10:11], off
	s_nop 0
	global_load_dwordx4 v[14:17], v[14:15], off
	s_nop 0
	global_load_dwordx4 v[18:21], v[18:19], off
	s_nop 0
	global_load_dwordx4 v[22:25], v[22:23], off
	v_or_b32_e32 v26, s16, v77
	v_lshlrev_b32_e32 v32, 10, v26
	v_lshl_add_u64 v[26:27], v[52:53], 0, v[32:33]
	v_or_b32_e32 v32, s16, v79
	global_load_dwordx4 v[26:29], v[26:27], off
	v_lshlrev_b32_e32 v32, 10, v32
	v_lshl_add_u64 v[52:53], v[52:53], 0, v[32:33]
	global_load_dwordx4 v[52:55], v[52:53], off
	s_lshl_b32 s14, s16, 1
	s_add_u32 s14, s10, s14
	s_addc_u32 s15, s1, 0
	v_lshlrev_b32_e32 v32, 1, v34
	v_readlane_b32 s41, v252, 17
	v_readlane_b32 s44, v252, 20
	v_readlane_b32 s45, v252, 21
	v_readlane_b32 s46, v252, 22
	v_readlane_b32 s47, v252, 23
	v_readlane_b32 s48, v252, 24
	v_readlane_b32 s49, v252, 25
	v_readlane_b32 s50, v252, 26
	v_readlane_b32 s51, v252, 27
	v_readlane_b32 s52, v252, 28
	v_readlane_b32 s53, v252, 29
	v_readlane_b32 s54, v252, 30
	v_readlane_b32 s55, v252, 31
	s_waitcnt vmcnt(7)
	ds_write2_b32 v31, v2, v3 offset1:1
	ds_write2_b32 v31, v4, v5 offset0:2 offset1:3
	s_waitcnt vmcnt(6)
	ds_write2_b32 v87, v6, v7 offset1:1
	ds_write2_b32 v88, v8, v9 offset1:1
	s_waitcnt vmcnt(5)
	ds_write2_b32 v89, v10, v11 offset1:1
	ds_write2_b32 v90, v12, v13 offset1:1
	s_waitcnt vmcnt(4)
	ds_write2_b32 v91, v14, v15 offset1:1
	ds_write2_b32 v92, v16, v17 offset1:1
	s_waitcnt vmcnt(3)
	ds_write2_b32 v93, v18, v19 offset1:1
	ds_write2_b32 v94, v20, v21 offset1:1
	s_waitcnt vmcnt(2)
	ds_write2_b32 v95, v22, v23 offset1:1
	ds_write2_b32 v96, v24, v25 offset1:1
	s_waitcnt vmcnt(1)
	ds_write2_b32 v97, v26, v27 offset1:1
	ds_write2_b32 v98, v28, v29 offset1:1
	s_waitcnt vmcnt(0)
	ds_write2_b32 v99, v52, v53 offset1:1
	ds_write2_b32 v100, v54, v55 offset1:1
	s_waitcnt lgkmcnt(0)
	ds_read2_b32 v[148:149], v81 offset1:33
	ds_read2_b32 v[150:151], v81 offset0:66 offset1:99
	ds_read2_b32 v[152:153], v81 offset0:132 offset1:165
	ds_read2_b32 v[154:155], v81 offset0:198 offset1:231
	ds_read2_b32 v[156:157], v81 offset0:8 offset1:41
	ds_read2_b32 v[158:159], v81 offset0:74 offset1:107
	ds_read2_b32 v[160:161], v81 offset0:140 offset1:173
	ds_read2_b32 v[162:163], v81 offset0:206 offset1:239
	ds_read2_b32 v[164:165], v81 offset0:16 offset1:49
	ds_read2_b32 v[166:167], v81 offset0:82 offset1:115
	ds_read2_b32 v[168:169], v81 offset0:148 offset1:181
	ds_read2_b32 v[170:171], v81 offset0:214 offset1:247
	ds_read2_b32 v[172:173], v81 offset0:24 offset1:57
	ds_read2_b32 v[174:175], v81 offset0:90 offset1:123
	ds_read2_b32 v[176:177], v81 offset0:156 offset1:189
	ds_read2_b32 v[178:179], v81 offset0:222 offset1:255
	s_waitcnt lgkmcnt(0)
	v_cvt_pk_bf16_f32 v180, v148, v149
	v_or_b32_e32 v10, s0, v1
	v_cvt_pk_bf16_f32 v181, v150, v151
	v_lshl_add_u64 v[8:9], s[14:15], 0, v[32:33]
	v_lshlrev_b32_e32 v32, 12, v10
	v_cvt_pk_bf16_f32 v182, v152, v153
	v_cvt_pk_bf16_f32 v183, v154, v155
	v_lshl_add_u64 v[10:11], v[8:9], 0, v[32:33]
	global_store_dwordx4 v[10:11], v[180:183], off
	v_or_b32_e32 v10, s0, v67
	v_lshlrev_b32_e32 v32, 12, v10
	v_cvt_pk_bf16_f32 v184, v156, v157
	v_cvt_pk_bf16_f32 v185, v158, v159
	v_cvt_pk_bf16_f32 v186, v160, v161
	v_cvt_pk_bf16_f32 v187, v162, v163
	v_lshl_add_u64 v[10:11], v[8:9], 0, v[32:33]
	global_store_dwordx4 v[10:11], v[184:187], off
	v_or_b32_e32 v10, s0, v69
	v_lshlrev_b32_e32 v32, 12, v10
	v_cvt_pk_bf16_f32 v188, v164, v165
	v_cvt_pk_bf16_f32 v189, v166, v167
	v_cvt_pk_bf16_f32 v190, v168, v169
	v_cvt_pk_bf16_f32 v191, v170, v171
	v_lshl_add_u64 v[10:11], v[8:9], 0, v[32:33]
	global_store_dwordx4 v[10:11], v[188:191], off
	s_nop 0
	v_cvt_pk_bf16_f32 v192, v172, v173
	v_cvt_pk_bf16_f32 v193, v174, v175
	v_cvt_pk_bf16_f32 v194, v176, v177
	v_or_b32_e32 v5, s0, v71
	v_lshlrev_b32_e32 v32, 12, v5
	v_cvt_pk_bf16_f32 v195, v178, v179
	v_lshl_add_u64 v[6:7], v[8:9], 0, v[32:33]
	global_store_dwordx4 v[6:7], v[192:195], off
	s_waitcnt lgkmcnt(0)

; #define LAS __attribute__((address_space(3)))
; __device__ __forceinline__ unsigned pk2(float lo, float hi) { return pg8::cvt_pk_bf16(lo, hi); }
; __device__ __forceinline__ void transpose_item(const float* W, int ldw, int nvalid, int K, bf16* WT, int k0, int n0, int drow0, LAS float* scr, int lane) {
;     const int r8 = lane >> 3, c4 = lane & 7;
; #pragma unroll
;     for (int i = 0; i < 8; ++i) { const int kk = 8 * i + r8; const int n = n0 + 4 * c4;
;         f32x4 v = {0.f, 0.f, 0.f, 0.f};
;         if (n < nvalid) v = *(const f32x4*)(W + (size_t)(k0 + kk) * ldw + n);
;         LAS float* d = scr + kk * 33 + 4 * c4; d[0] = v.x; d[1] = v.y; d[2] = v.z; d[3] = v.w; }
;     asm volatile("s_waitcnt lgkmcnt(0)" ::: "memory");
;     const int c = lane & 7;
; #pragma unroll
;     for (int j = 0; j < 4; ++j) { const int n = (lane >> 3) + 8 * j; const LAS float* s = scr + (8 * c) * 33 + n;
;         u32x4 o; o.x = pk2(s[0 * 33], s[1 * 33]); o.y = pk2(s[2 * 33], s[3 * 33]); o.z = pk2(s[4 * 33], s[5 * 33]); o.w = pk2(s[6 * 33], s[7 * 33]);
;         *(u32x4*)(WT + (size_t)(drow0 + n) * K + k0 + 8 * c) = o; }
;     asm volatile("s_waitcnt lgkmcnt(0)" ::: "memory");
; }
; __device__ __forceinline__ void transpose_plain(const float* W, int K, int N, int Npad, bf16* WT, int item, LAS float* scr, int lane) {
;     const int nblk = Npad / 32, kb = item / nblk, nb = item % nblk;
;     transpose_item(W, N, N, K, WT, 64 * kb, 32 * nb, 32 * nb, scr, lane);
.LBB0_33:
	s_andn2_b64 vcc, exec, s[0:1]
	s_cbranch_vccnz .LBB0_35
	s_add_i32 s16, s39, 0xffff6c40
	s_lshr_b32 s10, s16, 9
	v_readlane_b32 s40, v252, 16
	s_lshl_b64 s[0:1], s[10:11], 22
	v_readlane_b32 s46, v252, 22
	v_readlane_b32 s47, v252, 23
	s_add_u32 s14, s46, s0
	s_addc_u32 s15, s47, s1
	s_lshl_b64 s[0:1], s[10:11], 21
	v_readlane_b32 s10, v252, 40
	s_add_u32 s10, s10, s0
	v_readlane_b32 s0, v252, 41
	s_addc_u32 s1, s0, s1
	s_lshl_b32 s0, s16, 1
	s_and_b32 s16, s0, 0x3c0
	s_lshl_b32 s0, s39, 5
	s_and_b32 s0, s0, 0x3e0
	v_or_b32_e32 v2, s0, v65
	v_lshlrev_b32_e32 v32, 2, v2
	v_or_b32_e32 v2, s16, v1
	v_lshl_add_u64 v[52:53], s[14:15], 0, v[32:33]
	v_lshlrev_b32_e32 v32, 12, v2
	v_or_b32_e32 v4, s16, v67
	v_lshl_add_u64 v[2:3], v[52:53], 0, v[32:33]
	v_lshlrev_b32_e32 v32, 12, v4
	v_or_b32_e32 v10, s16, v69
	v_lshl_add_u64 v[6:7], v[52:53], 0, v[32:33]
	v_lshlrev_b32_e32 v32, 12, v10
	v_or_b32_e32 v12, s16, v71
	v_lshl_add_u64 v[10:11], v[52:53], 0, v[32:33]
	v_lshlrev_b32_e32 v32, 12, v12
	v_or_b32_e32 v18, s16, v73
	v_lshl_add_u64 v[14:15], v[52:53], 0, v[32:33]
	v_lshlrev_b32_e32 v32, 12, v18
	v_or_b32_e32 v20, s16, v75
	v_lshl_add_u64 v[18:19], v[52:53], 0, v[32:33]
	v_lshlrev_b32_e32 v32, 12, v20
	v_lshl_add_u64 v[22:23], v[52:53], 0, v[32:33]
	global_load_dwordx4 v[2:5], v[2:3], off
	s_nop 0
	global_load_dwordx4 v[6:9], v[6:7], off
	s_nop 0
	global_load_dwordx4 v[10:13], v[10:11], off
	s_nop 0
	global_load_dwordx4 v[14:17], v[14:15], off
	s_nop 0
	global_load_dwordx4 v[18:21], v[18:19], off
	s_nop 0
	global_load_dwordx4 v[22:25], v[22:23], off
	v_or_b32_e32 v26, s16, v77
	v_lshlrev_b32_e32 v32, 12, v26
	v_lshl_add_u64 v[26:27], v[52:53], 0, v[32:33]
	v_or_b32_e32 v32, s16, v79
	global_load_dwordx4 v[26:29], v[26:27], off
	v_lshlrev_b32_e32 v32, 12, v32
	v_lshl_add_u64 v[52:53], v[52:53], 0, v[32:33]
	global_load_dwordx4 v[52:55], v[52:53], off
	s_lshl_b32 s14, s16, 1
	s_add_u32 s14, s10, s14
	s_addc_u32 s15, s1, 0
	v_lshlrev_b32_e32 v32, 1, v34
	v_readlane_b32 s41, v252, 17
	v_readlane_b32 s42, v252, 18
	v_readlane_b32 s43, v252, 19
	v_readlane_b32 s44, v252, 20
	v_readlane_b32 s45, v252, 21
	v_readlane_b32 s48, v252, 24
	v_readlane_b32 s49, v252, 25
	v_readlane_b32 s50, v252, 26
	v_readlane_b32 s51, v252, 27
	v_readlane_b32 s52, v252, 28
	v_readlane_b32 s53, v252, 29
	v_readlane_b32 s54, v252, 30
	v_readlane_b32 s55, v252, 31
	s_waitcnt vmcnt(7)
	ds_write2_b32 v31, v2, v3 offset1:1
	ds_write2_b32 v31, v4, v5 offset0:2 offset1:3
	s_waitcnt vmcnt(6)
	ds_write2_b32 v87, v6, v7 offset1:1
	ds_write2_b32 v88, v8, v9 offset1:1
	s_waitcnt vmcnt(5)
	ds_write2_b32 v89, v10, v11 offset1:1
	ds_write2_b32 v90, v12, v13 offset1:1
	s_waitcnt vmcnt(4)
	ds_write2_b32 v91, v14, v15 offset1:1
	ds_write2_b32 v92, v16, v17 offset1:1
	s_waitcnt vmcnt(3)
	ds_write2_b32 v93, v18, v19 offset1:1
	ds_write2_b32 v94, v20, v21 offset1:1
	s_waitcnt vmcnt(2)
	ds_write2_b32 v95, v22, v23 offset1:1
	ds_write2_b32 v96, v24, v25 offset1:1
	s_waitcnt vmcnt(1)
	ds_write2_b32 v97, v26, v27 offset1:1
	ds_write2_b32 v98, v28, v29 offset1:1
	s_waitcnt vmcnt(0)
	ds_write2_b32 v99, v52, v53 offset1:1
	ds_write2_b32 v100, v54, v55 offset1:1
	s_waitcnt lgkmcnt(0)
	ds_read2_b32 v[148:149], v81 offset1:33
	ds_read2_b32 v[150:151], v81 offset0:66 offset1:99
	ds_read2_b32 v[152:153], v81 offset0:132 offset1:165
	ds_read2_b32 v[154:155], v81 offset0:198 offset1:231
	ds_read2_b32 v[156:157], v81 offset0:8 offset1:41
	ds_read2_b32 v[158:159], v81 offset0:74 offset1:107
	ds_read2_b32 v[160:161], v81 offset0:140 offset1:173
	ds_read2_b32 v[162:163], v81 offset0:206 offset1:239
	ds_read2_b32 v[164:165], v81 offset0:16 offset1:49
	ds_read2_b32 v[166:167], v81 offset0:82 offset1:115
	ds_read2_b32 v[168:169], v81 offset0:148 offset1:181
	ds_read2_b32 v[170:171], v81 offset0:214 offset1:247
	ds_read2_b32 v[172:173], v81 offset0:24 offset1:57
	ds_read2_b32 v[174:175], v81 offset0:90 offset1:123
	ds_read2_b32 v[176:177], v81 offset0:156 offset1:189
	ds_read2_b32 v[178:179], v81 offset0:222 offset1:255
	s_waitcnt lgkmcnt(0)
	v_cvt_pk_bf16_f32 v180, v148, v149
	v_or_b32_e32 v10, s0, v1
	v_cvt_pk_bf16_f32 v181, v150, v151
	v_lshl_add_u64 v[8:9], s[14:15], 0, v[32:33]
	v_lshlrev_b32_e32 v32, 11, v10
	v_cvt_pk_bf16_f32 v182, v152, v153
	v_cvt_pk_bf16_f32 v183, v154, v155
	v_lshl_add_u64 v[10:11], v[8:9], 0, v[32:33]
	global_store_dwordx4 v[10:11], v[180:183], off
	v_or_b32_e32 v10, s0, v67
	v_lshlrev_b32_e32 v32, 11, v10
	v_cvt_pk_bf16_f32 v184, v156, v157
	v_cvt_pk_bf16_f32 v185, v158, v159
	v_cvt_pk_bf16_f32 v186, v160, v161
	v_cvt_pk_bf16_f32 v187, v162, v163
	v_lshl_add_u64 v[10:11], v[8:9], 0, v[32:33]
	global_store_dwordx4 v[10:11], v[184:187], off
	v_or_b32_e32 v10, s0, v69
	v_lshlrev_b32_e32 v32, 11, v10
	v_cvt_pk_bf16_f32 v188, v164, v165
	v_cvt_pk_bf16_f32 v189, v166, v167
	v_cvt_pk_bf16_f32 v190, v168, v169
	v_cvt_pk_bf16_f32 v191, v170, v171
	v_lshl_add_u64 v[10:11], v[8:9], 0, v[32:33]
	global_store_dwordx4 v[10:11], v[188:191], off
	s_nop 0
	v_cvt_pk_bf16_f32 v192, v172, v173
	v_cvt_pk_bf16_f32 v193, v174, v175
	v_cvt_pk_bf16_f32 v194, v176, v177
	v_or_b32_e32 v5, s0, v71
	v_lshlrev_b32_e32 v32, 11, v5
	v_cvt_pk_bf16_f32 v195, v178, v179
	v_lshl_add_u64 v[6:7], v[8:9], 0, v[32:33]
	global_store_dwordx4 v[6:7], v[192:195], off
	s_waitcnt lgkmcnt(0)

; #define LAS __attribute__((address_space(3)))
; __device__ __forceinline__ unsigned pk2(float lo, float hi) { return pg8::cvt_pk_bf16(lo, hi); }
; #define P0_TAKE(LAY) { if (lsel >= 0 && (LAY) != lsel) continue; const int kc_ = kcount++; if (half >= 0 && (kc_ & 1) != half) continue; }
; __device__ __forceinline__ void transpose_item(const float* W, int ldw, int nvalid, int K, bf16* WT, int k0, int n0, int drow0, LAS float* scr, int lane) {
;     const int r8 = lane >> 3, c4 = lane & 7;
; #pragma unroll
;     for (int i = 0; i < 8; ++i) { const int kk = 8 * i + r8; const int n = n0 + 4 * c4;
;         f32x4 v = {0.f, 0.f, 0.f, 0.f};
;         if (n < nvalid) v = *(const f32x4*)(W + (size_t)(k0 + kk) * ldw + n);
;         LAS float* d = scr + kk * 33 + 4 * c4; d[0] = v.x; d[1] = v.y; d[2] = v.z; d[3] = v.w; }
;     asm volatile("s_waitcnt lgkmcnt(0)" ::: "memory");
;     const int c = lane & 7;
; #pragma unroll
;     for (int j = 0; j < 4; ++j) { const int n = (lane >> 3) + 8 * j; const LAS float* s = scr + (8 * c) * 33 + n;
;         u32x4 o; o.x = pk2(s[0 * 33], s[1 * 33]); o.y = pk2(s[2 * 33], s[3 * 33]); o.z = pk2(s[4 * 33], s[5 * 33]); o.w = pk2(s[6 * 33], s[7 * 33]);
;         *(u32x4*)(WT + (size_t)(drow0 + n) * K + k0 + 8 * c) = o; }
;     asm volatile("s_waitcnt lgkmcnt(0)" ::: "memory");
; }
; __device__ __forceinline__ void p0_prologue(const Args& A, LAS unsigned char* lds, int gw, int NGW, int wave, int lane, int lsel, int half) {
;     ...
;         if (r < I_IN3) { P0_TAKE(1) transpose_plain(A.in[12], D, 3 * D, 3 * D, (bf16*)(ws + WS_SBIN), r, scr, lane); continue; }
;         r -= I_IN3;
;         if (r < I_IN3) { P0_TAKE(2) transpose_plain(A.in[14], D, 3 * D, 3 * D, (bf16*)(ws + WS_DFIN), r, scr, lane); continue; }
;         r -= I_IN3;
;         if (r < I_SQ) { P0_TAKE(1) transpose_plain(A.in[13], D, D, D, (bf16*)(ws + WS_SBOUT), r, scr, lane); continue; }
;         r -= I_SQ;
;         P0_TAKE(2)
;         transpose_plain(A.in[17], D, D, D, (bf16*)(ws + WS_DFOUT), r, scr, lane);
.LBB0_45:
	s_or_b64 exec, exec, s[14:15]
	s_and_b64 s[0:1], s[0:1], exec
	s_cselect_b32 s0, 0x580000, 0
	v_readlane_b32 s1, v252, 42
	s_waitcnt vmcnt(1)
	ds_write2_b32 v97, v6, v7 offset1:1
	ds_write2_b32 v98, v8, v9 offset1:1
	s_waitcnt vmcnt(0)
	ds_write2_b32 v99, v2, v3 offset1:1
	ds_write2_b32 v100, v4, v5 offset1:1
	s_add_u32 s0, s1, s0
	v_readlane_b32 s1, v252, 43
	s_waitcnt lgkmcnt(0)
	s_addc_u32 s1, s1, 0
	s_lshl_b32 s14, s18, 1
	ds_read2_b32 v[148:149], v81 offset1:33
	ds_read2_b32 v[150:151], v81 offset0:66 offset1:99
	ds_read2_b32 v[152:153], v81 offset0:132 offset1:165
	ds_read2_b32 v[154:155], v81 offset0:198 offset1:231
	ds_read2_b32 v[156:157], v81 offset0:8 offset1:41
	ds_read2_b32 v[158:159], v81 offset0:74 offset1:107
	ds_read2_b32 v[160:161], v81 offset0:140 offset1:173
	ds_read2_b32 v[162:163], v81 offset0:206 offset1:239
	ds_read2_b32 v[164:165], v81 offset0:16 offset1:49
	ds_read2_b32 v[166:167], v81 offset0:82 offset1:115
	ds_read2_b32 v[168:169], v81 offset0:148 offset1:181
	ds_read2_b32 v[170:171], v81 offset0:214 offset1:247
	ds_read2_b32 v[172:173], v81 offset0:24 offset1:57
	ds_read2_b32 v[174:175], v81 offset0:90 offset1:123
	ds_read2_b32 v[176:177], v81 offset0:156 offset1:189
	ds_read2_b32 v[178:179], v81 offset0:222 offset1:255
	s_waitcnt lgkmcnt(0)
	s_add_u32 s0, s0, s14
	v_cvt_pk_bf16_f32 v180, v148, v149
	v_lshlrev_b32_e32 v32, 1, v34
	v_or_b32_e32 v10, s10, v1
	s_addc_u32 s1, s1, 0
	v_cvt_pk_bf16_f32 v181, v150, v151
	v_lshl_add_u64 v[8:9], s[0:1], 0, v[32:33]
	v_lshlrev_b32_e32 v32, 11, v10
	v_cvt_pk_bf16_f32 v182, v152, v153
	v_cvt_pk_bf16_f32 v183, v154, v155
	v_lshl_add_u64 v[10:11], v[8:9], 0, v[32:33]
	global_store_dwordx4 v[10:11], v[180:183], off
	v_or_b32_e32 v10, s10, v67
	v_lshlrev_b32_e32 v32, 11, v10
	v_cvt_pk_bf16_f32 v184, v156, v157
	v_cvt_pk_bf16_f32 v185, v158, v159
	v_cvt_pk_bf16_f32 v186, v160, v161
	v_cvt_pk_bf16_f32 v187, v162, v163
	v_lshl_add_u64 v[10:11], v[8:9], 0, v[32:33]
	global_store_dwordx4 v[10:11], v[184:187], off
	v_or_b32_e32 v10, s10, v69
	v_lshlrev_b32_e32 v32, 11, v10
	v_cvt_pk_bf16_f32 v188, v164, v165
	v_cvt_pk_bf16_f32 v189, v166, v167
	v_cvt_pk_bf16_f32 v190, v168, v169
	v_cvt_pk_bf16_f32 v191, v170, v171
	v_lshl_add_u64 v[10:11], v[8:9], 0, v[32:33]
	global_store_dwordx4 v[10:11], v[188:191], off
	s_nop 0
	v_cvt_pk_bf16_f32 v192, v172, v173
	v_cvt_pk_bf16_f32 v193, v174, v175
	v_cvt_pk_bf16_f32 v194, v176, v177
	v_or_b32_e32 v5, s10, v71
	v_lshlrev_b32_e32 v32, 11, v5
	v_cvt_pk_bf16_f32 v195, v178, v179
	v_lshl_add_u64 v[6:7], v[8:9], 0, v[32:33]
	global_store_dwordx4 v[6:7], v[192:195], off
	s_waitcnt lgkmcnt(0)

; #define LAS __attribute__((address_space(3)))
; __device__ __forceinline__ unsigned pk2(float lo, float hi) { return pg8::cvt_pk_bf16(lo, hi); }
; #define P0_TAKE(LAY) { if (lsel >= 0 && (LAY) != lsel) continue; const int kc_ = kcount++; if (half >= 0 && (kc_ & 1) != half) continue; }
; __device__ __forceinline__ void transpose_item(const float* W, int ldw, int nvalid, int K, bf16* WT, int k0, int n0, int drow0, LAS float* scr, int lane) {
;     const int r8 = lane >> 3, c4 = lane & 7;
; #pragma unroll
;     for (int i = 0; i < 8; ++i) { const int kk = 8 * i + r8; const int n = n0 + 4 * c4;
;         f32x4 v = {0.f, 0.f, 0.f, 0.f};
;         if (n < nvalid) v = *(const f32x4*)(W + (size_t)(k0 + kk) * ldw + n);
;         LAS float* d = scr + kk * 33 + 4 * c4; d[0] = v.x; d[1] = v.y; d[2] = v.z; d[3] = v.w; }
;     asm volatile("s_waitcnt lgkmcnt(0)" ::: "memory");
;     const int c = lane & 7;
; #pragma unroll
;     for (int j = 0; j < 4; ++j) { const int n = (lane >> 3) + 8 * j; const LAS float* s = scr + (8 * c) * 33 + n;
;         u32x4 o; o.x = pk2(s[0 * 33], s[1 * 33]); o.y = pk2(s[2 * 33], s[3 * 33]); o.z = pk2(s[4 * 33], s[5 * 33]); o.w = pk2(s[6 * 33], s[7 * 33]);
;         *(u32x4*)(WT + (size_t)(drow0 + n) * K + k0 + 8 * c) = o; }
;     asm volatile("s_waitcnt lgkmcnt(0)" ::: "memory");
; }
; __device__ __forceinline__ void p0_prologue(const Args& A, LAS unsigned char* lds, int gw, int NGW, int wave, int lane, int lsel, int half) {
;     ...
;         if (r < 8 * I_W2) { const int sub = r / I_W2; P0_TAKE(sub >> 1) transpose_plain(A.in[6] + (size_t)sub * DFF * D, DFF, D, D, (bf16*)(ws + WS_W2T) + (size_t)sub * D * DFF, r % I_W2, scr, lane); continue; }
.LBB0_47:
	s_andn2_b64 vcc, exec, s[0:1]
	s_cbranch_vccnz .LBB0_49
	s_add_i32 s0, s39, 0xa340
	s_and_b32 s1, s0, 0xffff
	s_mul_i32 s1, s1, 0xba2f
	s_lshr_b32 s1, s1, 26
	v_readlane_b32 s40, v252, 0
	s_mul_i32 s10, s1, 0xb00000
	v_readlane_b32 s52, v252, 12
	v_readlane_b32 s53, v252, 13
	s_add_u32 s14, s52, s10
	s_addc_u32 s15, s53, 0
	s_mul_i32 s10, s1, 0x580000
	v_readlane_b32 s16, v252, 44
	s_add_u32 s10, s16, s10
	v_readlane_b32 s16, v252, 45
	s_mulk_i32 s1, 0x580
	s_addc_u32 s16, s16, 0
	s_sub_i32 s0, s0, s1
	s_lshl_b32 s1, s0, 1
	s_lshl_b32 s0, s0, 5
	s_and_b32 s0, s0, 0x3e0
	s_and_b32 s1, s1, 0xfc0
	v_or_b32_e32 v2, s0, v65
	v_lshlrev_b32_e32 v32, 2, v2
	v_or_b32_e32 v2, s1, v1
	v_lshl_add_u64 v[52:53], s[14:15], 0, v[32:33]
	v_lshlrev_b32_e32 v32, 12, v2
	v_or_b32_e32 v4, s1, v67
	v_lshl_add_u64 v[2:3], v[52:53], 0, v[32:33]
	v_lshlrev_b32_e32 v32, 12, v4
	v_or_b32_e32 v10, s1, v69
	v_lshl_add_u64 v[6:7], v[52:53], 0, v[32:33]
	v_lshlrev_b32_e32 v32, 12, v10
	v_or_b32_e32 v12, s1, v71
	v_lshl_add_u64 v[10:11], v[52:53], 0, v[32:33]
	v_lshlrev_b32_e32 v32, 12, v12
	v_or_b32_e32 v18, s1, v73
	v_lshl_add_u64 v[14:15], v[52:53], 0, v[32:33]
	v_lshlrev_b32_e32 v32, 12, v18
	v_or_b32_e32 v20, s1, v75
	v_lshl_add_u64 v[18:19], v[52:53], 0, v[32:33]
	v_lshlrev_b32_e32 v32, 12, v20
	v_lshl_add_u64 v[22:23], v[52:53], 0, v[32:33]
	global_load_dwordx4 v[2:5], v[2:3], off
	s_nop 0
	global_load_dwordx4 v[6:9], v[6:7], off
	s_nop 0
	global_load_dwordx4 v[10:13], v[10:11], off
	s_nop 0
	global_load_dwordx4 v[14:17], v[14:15], off
	s_nop 0
	global_load_dwordx4 v[18:21], v[18:19], off
	s_nop 0
	global_load_dwordx4 v[22:25], v[22:23], off
	v_or_b32_e32 v26, s1, v77
	v_lshlrev_b32_e32 v32, 12, v26
	v_lshl_add_u64 v[26:27], v[52:53], 0, v[32:33]
	v_or_b32_e32 v32, s1, v79
	global_load_dwordx4 v[26:29], v[26:27], off
	v_lshlrev_b32_e32 v32, 12, v32
	v_lshl_add_u64 v[52:53], v[52:53], 0, v[32:33]
	global_load_dwordx4 v[52:55], v[52:53], off
	s_lshl_b32 s1, s1, 1
	s_add_u32 s14, s10, s1
	s_addc_u32 s15, s16, 0
	v_lshlrev_b32_e32 v32, 1, v34
	v_readlane_b32 s41, v252, 1
	v_readlane_b32 s42, v252, 2
	v_readlane_b32 s43, v252, 3
	v_readlane_b32 s44, v252, 4
	v_readlane_b32 s45, v252, 5
	v_readlane_b32 s46, v252, 6
	v_readlane_b32 s47, v252, 7
	v_readlane_b32 s48, v252, 8
	v_readlane_b32 s49, v252, 9
	v_readlane_b32 s50, v252, 10
	v_readlane_b32 s51, v252, 11
	v_readlane_b32 s54, v252, 14
	v_readlane_b32 s55, v252, 15
	s_waitcnt vmcnt(7)
	ds_write2_b32 v31, v2, v3 offset1:1
	ds_write2_b32 v31, v4, v5 offset0:2 offset1:3
	s_waitcnt vmcnt(6)
	ds_write2_b32 v87, v6, v7 offset1:1
	ds_write2_b32 v88, v8, v9 offset1:1
	s_waitcnt vmcnt(5)
	ds_write2_b32 v89, v10, v11 offset1:1
	ds_write2_b32 v90, v12, v13 offset1:1
	s_waitcnt vmcnt(4)
	ds_write2_b32 v91, v14, v15 offset1:1
	ds_write2_b32 v92, v16, v17 offset1:1
	s_waitcnt vmcnt(3)
	ds_write2_b32 v93, v18, v19 offset1:1
	ds_write2_b32 v94, v20, v21 offset1:1
	s_waitcnt vmcnt(2)
	ds_write2_b32 v95, v22, v23 offset1:1
	ds_write2_b32 v96, v24, v25 offset1:1
	s_waitcnt vmcnt(1)
	ds_write2_b32 v97, v26, v27 offset1:1
	ds_write2_b32 v98, v28, v29 offset1:1
	s_waitcnt vmcnt(0)
	ds_write2_b32 v99, v52, v53 offset1:1
	ds_write2_b32 v100, v54, v55 offset1:1
	s_waitcnt lgkmcnt(0)
	v_or_b32_e32 v8, s0, v1
	ds_read2_b32 v[148:149], v81 offset1:33
	ds_read2_b32 v[150:151], v81 offset0:66 offset1:99
	ds_read2_b32 v[152:153], v81 offset0:132 offset1:165
	ds_read2_b32 v[154:155], v81 offset0:198 offset1:231
	ds_read2_b32 v[156:157], v81 offset0:8 offset1:41
	ds_read2_b32 v[158:159], v81 offset0:74 offset1:107
	ds_read2_b32 v[160:161], v81 offset0:140 offset1:173
	ds_read2_b32 v[162:163], v81 offset0:206 offset1:239
	ds_read2_b32 v[164:165], v81 offset0:16 offset1:49
	ds_read2_b32 v[166:167], v81 offset0:82 offset1:115
	ds_read2_b32 v[168:169], v81 offset0:148 offset1:181
	ds_read2_b32 v[170:171], v81 offset0:214 offset1:247
	ds_read2_b32 v[172:173], v81 offset0:24 offset1:57
	ds_read2_b32 v[174:175], v81 offset0:90 offset1:123
	ds_read2_b32 v[176:177], v81 offset0:156 offset1:189
	ds_read2_b32 v[178:179], v81 offset0:222 offset1:255
	s_waitcnt lgkmcnt(0)
	v_mul_u32_u24_e32 v10, 0xb00, v8
	v_cvt_pk_bf16_f32 v180, v148, v149
	v_lshl_add_u64 v[8:9], s[14:15], 0, v[32:33]
	v_lshlrev_b32_e32 v32, 1, v10
	v_cvt_pk_bf16_f32 v181, v150, v151
	v_lshl_add_u64 v[10:11], v[8:9], 0, v[32:33]
	v_cvt_pk_bf16_f32 v182, v152, v153
	v_cvt_pk_bf16_f32 v183, v154, v155
	global_store_dwordx4 v[10:11], v[180:183], off
	v_or_b32_e32 v10, s0, v67
	v_mul_u32_u24_e32 v10, 0xb00, v10
	v_cvt_pk_bf16_f32 v184, v156, v157
	v_lshlrev_b32_e32 v32, 1, v10
	v_cvt_pk_bf16_f32 v185, v158, v159
	v_lshl_add_u64 v[10:11], v[8:9], 0, v[32:33]
	v_cvt_pk_bf16_f32 v186, v160, v161
	v_cvt_pk_bf16_f32 v187, v162, v163
	global_store_dwordx4 v[10:11], v[184:187], off
	v_or_b32_e32 v10, s0, v69
	v_cvt_pk_bf16_f32 v188, v164, v165
	v_mul_u32_u24_e32 v10, 0xb00, v10
	v_cvt_pk_bf16_f32 v189, v166, v167
	v_lshlrev_b32_e32 v32, 1, v10
	v_cvt_pk_bf16_f32 v190, v168, v169
	v_cvt_pk_bf16_f32 v191, v170, v171
	v_lshl_add_u64 v[10:11], v[8:9], 0, v[32:33]
	global_store_dwordx4 v[10:11], v[188:191], off
	s_nop 0
	v_cvt_pk_bf16_f32 v192, v172, v173
	v_cvt_pk_bf16_f32 v193, v174, v175
	v_cvt_pk_bf16_f32 v194, v176, v177
	v_or_b32_e32 v5, s0, v71
	v_mul_u32_u24_e32 v5, 0xb00, v5
	v_lshlrev_b32_e32 v32, 1, v5
	v_cvt_pk_bf16_f32 v195, v178, v179
	v_lshl_add_u64 v[6:7], v[8:9], 0, v[32:33]
	global_store_dwordx4 v[6:7], v[192:195], off
	s_waitcnt lgkmcnt(0)

; #define LAS __attribute__((address_space(3)))
; __device__ __forceinline__ unsigned pk2(float lo, float hi) { return pg8::cvt_pk_bf16(lo, hi); }
; #define P0_TAKE(LAY) { if (lsel >= 0 && (LAY) != lsel) continue; const int kc_ = kcount++; if (half >= 0 && (kc_ & 1) != half) continue; }
; __device__ __forceinline__ void transpose_item(const float* W, int ldw, int nvalid, int K, bf16* WT, int k0, int n0, int drow0, LAS float* scr, int lane) {
;     const int r8 = lane >> 3, c4 = lane & 7;
; #pragma unroll
;     for (int i = 0; i < 8; ++i) { const int kk = 8 * i + r8; const int n = n0 + 4 * c4;
;         f32x4 v = {0.f, 0.f, 0.f, 0.f};
;         if (n < nvalid) v = *(const f32x4*)(W + (size_t)(k0 + kk) * ldw + n);
;         LAS float* d = scr + kk * 33 + 4 * c4; d[0] = v.x; d[1] = v.y; d[2] = v.z; d[3] = v.w; }
;     asm volatile("s_waitcnt lgkmcnt(0)" ::: "memory");
;     const int c = lane & 7;
; #pragma unroll
;     for (int j = 0; j < 4; ++j) { const int n = (lane >> 3) + 8 * j; const LAS float* s = scr + (8 * c) * 33 + n;
;         u32x4 o; o.x = pk2(s[0 * 33], s[1 * 33]); o.y = pk2(s[2 * 33], s[3 * 33]); o.z = pk2(s[4 * 33], s[5 * 33]); o.w = pk2(s[6 * 33], s[7 * 33]);
;         *(u32x4*)(WT + (size_t)(drow0 + n) * K + k0 + 8 * c) = o; }
;     asm volatile("s_waitcnt lgkmcnt(0)" ::: "memory");
; }
; __device__ __forceinline__ void p0_prologue(const Args& A, LAS unsigned char* lds, int gw, int NGW, int wave, int lane, int lsel, int half) {
;     ...
;         if (r < 8 * I_W1) {
;             const int sub = r / I_W1, rr = r % I_W1, nblk = 2 * DFF / 32, kb = rr / nblk, nb = rr % nblk, n0 = 32 * nb;
;             P0_TAKE(sub >> 1)
;             const int n1 = n0 < DFF ? n0 : n0 - DFF; const int drow = (n1 / 128) * 256 + (n0 < DFF ? 0 : 128) + (n1 % 128);
;             transpose_item(A.in[5] + (size_t)sub * D * 2 * DFF, 2 * DFF, 2 * DFF, D, (bf16*)(ws + WS_W1T) + (size_t)sub * 2 * DFF * D, 64 * kb, n0, drow, scr, lane);
;             continue; }
.LBB0_50:
	s_andn2_b64 vcc, exec, s[0:1]
	s_cbranch_vccnz .LBB0_52
	s_add_i32 s0, s39, 0xfb40
	s_and_b32 s1, s0, 0xffff
	s_mul_i32 s1, s1, 0xba2f
	s_lshr_b32 s1, s1, 27
	s_mul_i32 s10, s1, 0xb00
	s_sub_i32 s0, s0, s10
	s_and_b32 s10, s0, 0xffff
	s_mul_i32 s10, s10, 0xba2f
	s_lshr_b32 s10, s10, 23
	s_mul_i32 s14, s10, 0xb0
	s_sub_i32 s0, s0, s14
	s_lshl_b32 s14, s0, 5
	s_and_b32 s16, s14, 0xffe0
	s_and_b32 s0, s0, 0xffff
	s_add_i32 s15, s14, 0xf500
	s_cmpk_lt_u32 s0, 0x58
	s_cselect_b32 s0, s14, s15
	s_sext_i32_i16 s14, s0
	s_cselect_b32 s15, 0, 0x80
	s_bfe_u32 s14, s14, 0x70018
	s_add_i32 s14, s0, s14
	s_sext_i32_i16 s17, s14
	s_and_b32 s14, s14, 0xff80
	s_sub_i32 s0, s0, s14
	s_lshl_b32 s17, s17, 1
	s_sext_i32_i16 s0, s0
	s_and_b32 s17, s17, 0xffffff00
	s_add_i32 s0, s15, s0
	v_readlane_b32 s40, v252, 0
	s_add_i32 s0, s0, s17
	s_mul_i32 s14, s1, 0x1600000
	v_readlane_b32 s50, v252, 10
	v_readlane_b32 s51, v252, 11
	s_add_u32 s14, s50, s14
	s_addc_u32 s15, s51, 0
	s_mul_i32 s1, s1, 0xb00000
	v_readlane_b32 s17, v252, 46
	s_add_u32 s1, s17, s1
	v_readlane_b32 s17, v252, 47
	s_addc_u32 s17, s17, 0
	s_lshl_b32 s18, s10, 6
	v_or_b32_e32 v2, s16, v65
	v_lshlrev_b32_e32 v32, 2, v2
	v_or_b32_e32 v2, s18, v1
	v_mul_u32_u24_e32 v2, 0x1600, v2
	v_or_b32_e32 v4, s18, v67
	v_lshl_add_u64 v[52:53], s[14:15], 0, v[32:33]
	v_lshlrev_b32_e32 v32, 2, v2
	v_mul_u32_u24_e32 v4, 0x1600, v4
	v_or_b32_e32 v10, s18, v69
	v_lshl_add_u64 v[2:3], v[52:53], 0, v[32:33]
	v_lshlrev_b32_e32 v32, 2, v4
	v_mul_u32_u24_e32 v10, 0x1600, v10
	v_or_b32_e32 v12, s18, v71
	v_lshl_add_u64 v[6:7], v[52:53], 0, v[32:33]
	v_lshlrev_b32_e32 v32, 2, v10
	v_mul_u32_u24_e32 v12, 0x1600, v12
	v_or_b32_e32 v18, s18, v73
	v_lshl_add_u64 v[10:11], v[52:53], 0, v[32:33]
	v_lshlrev_b32_e32 v32, 2, v12
	v_mul_u32_u24_e32 v18, 0x1600, v18
	v_or_b32_e32 v20, s18, v75
	v_lshl_add_u64 v[14:15], v[52:53], 0, v[32:33]
	v_lshlrev_b32_e32 v32, 2, v18
	v_mul_u32_u24_e32 v20, 0x1600, v20
	v_lshl_add_u64 v[18:19], v[52:53], 0, v[32:33]
	v_lshlrev_b32_e32 v32, 2, v20
	v_lshl_add_u64 v[22:23], v[52:53], 0, v[32:33]
	global_load_dwordx4 v[2:5], v[2:3], off
	s_nop 0
	global_load_dwordx4 v[6:9], v[6:7], off
	s_nop 0
	global_load_dwordx4 v[10:13], v[10:11], off
	s_nop 0
	global_load_dwordx4 v[14:17], v[14:15], off
	s_nop 0
	global_load_dwordx4 v[18:21], v[18:19], off
	s_nop 0
	global_load_dwordx4 v[22:25], v[22:23], off
	v_or_b32_e32 v26, s18, v77
	v_mul_u32_u24_e32 v26, 0x1600, v26
	v_lshlrev_b32_e32 v32, 2, v26
	v_lshl_add_u64 v[26:27], v[52:53], 0, v[32:33]
	v_or_b32_e32 v32, s18, v79
	v_mul_u32_u24_e32 v32, 0x1600, v32
	global_load_dwordx4 v[26:29], v[26:27], off
	v_lshlrev_b32_e32 v32, 2, v32
	v_lshl_add_u64 v[52:53], v[52:53], 0, v[32:33]
	global_load_dwordx4 v[52:55], v[52:53], off
	s_lshl_b32 s10, s10, 7
	s_add_u32 s14, s1, s10
	s_addc_u32 s15, s17, 0
	v_lshlrev_b32_e32 v32, 1, v34
	v_readlane_b32 s41, v252, 1
	v_readlane_b32 s42, v252, 2
	v_readlane_b32 s43, v252, 3
	v_readlane_b32 s44, v252, 4
	v_readlane_b32 s45, v252, 5
	v_readlane_b32 s46, v252, 6
	v_readlane_b32 s47, v252, 7
	v_readlane_b32 s48, v252, 8
	v_readlane_b32 s49, v252, 9
	v_readlane_b32 s52, v252, 12
	v_readlane_b32 s53, v252, 13
	v_readlane_b32 s54, v252, 14
	v_readlane_b32 s55, v252, 15
	s_waitcnt vmcnt(7)
	ds_write2_b32 v31, v2, v3 offset1:1
	ds_write2_b32 v31, v4, v5 offset0:2 offset1:3
	s_waitcnt vmcnt(6)
	ds_write2_b32 v87, v6, v7 offset1:1
	ds_write2_b32 v88, v8, v9 offset1:1
	s_waitcnt vmcnt(5)
	ds_write2_b32 v89, v10, v11 offset1:1
	ds_write2_b32 v90, v12, v13 offset1:1
	s_waitcnt vmcnt(4)
	ds_write2_b32 v91, v14, v15 offset1:1
	ds_write2_b32 v92, v16, v17 offset1:1
	s_waitcnt vmcnt(3)
	ds_write2_b32 v93, v18, v19 offset1:1
	ds_write2_b32 v94, v20, v21 offset1:1
	s_waitcnt vmcnt(2)
	ds_write2_b32 v95, v22, v23 offset1:1
	ds_write2_b32 v96, v24, v25 offset1:1
	s_waitcnt vmcnt(1)
	ds_write2_b32 v97, v26, v27 offset1:1
	ds_write2_b32 v98, v28, v29 offset1:1
	s_waitcnt vmcnt(0)
	ds_write2_b32 v99, v52, v53 offset1:1
	ds_write2_b32 v100, v54, v55 offset1:1
	s_waitcnt lgkmcnt(0)
	ds_read2_b32 v[148:149], v81 offset1:33
	ds_read2_b32 v[150:151], v81 offset0:66 offset1:99
	ds_read2_b32 v[152:153], v81 offset0:132 offset1:165
	ds_read2_b32 v[154:155], v81 offset0:198 offset1:231
	ds_read2_b32 v[156:157], v81 offset0:8 offset1:41
	ds_read2_b32 v[158:159], v81 offset0:74 offset1:107
	ds_read2_b32 v[160:161], v81 offset0:140 offset1:173
	ds_read2_b32 v[162:163], v81 offset0:206 offset1:239
	ds_read2_b32 v[164:165], v81 offset0:16 offset1:49
	ds_read2_b32 v[166:167], v81 offset0:82 offset1:115
	ds_read2_b32 v[168:169], v81 offset0:148 offset1:181
	ds_read2_b32 v[170:171], v81 offset0:214 offset1:247
	ds_read2_b32 v[172:173], v81 offset0:24 offset1:57
	ds_read2_b32 v[174:175], v81 offset0:90 offset1:123
	ds_read2_b32 v[176:177], v81 offset0:156 offset1:189
	ds_read2_b32 v[178:179], v81 offset0:222 offset1:255
	s_waitcnt lgkmcnt(0)
	v_cvt_pk_bf16_f32 v180, v148, v149
	v_add_u32_e32 v6, s0, v1
	v_cvt_pk_bf16_f32 v181, v150, v151
	v_ashrrev_i32_e32 v7, 31, v6
	v_cvt_pk_bf16_f32 v182, v152, v153
	v_lshlrev_b64 v[6:7], 11, v[6:7]
	v_lshl_add_u64 v[10:11], s[14:15], 0, v[32:33]
	v_cvt_pk_bf16_f32 v183, v154, v155
	v_lshl_add_u64 v[6:7], v[10:11], 0, v[6:7]
	global_store_dwordx4 v[6:7], v[180:183], off
	s_nop 0
	v_cvt_pk_bf16_f32 v184, v156, v157
	v_add_u32_e32 v8, s0, v67
	v_ashrrev_i32_e32 v9, 31, v8
	v_lshlrev_b64 v[8:9], 11, v[8:9]
	v_cvt_pk_bf16_f32 v185, v158, v159
	v_lshl_add_u64 v[8:9], v[10:11], 0, v[8:9]
	v_cvt_pk_bf16_f32 v186, v160, v161
	v_cvt_pk_bf16_f32 v187, v162, v163
	global_store_dwordx4 v[8:9], v[184:187], off
	v_add_u32_e32 v8, s0, v69
	v_cvt_pk_bf16_f32 v188, v164, v165
	v_ashrrev_i32_e32 v9, 31, v8
	v_cvt_pk_bf16_f32 v189, v166, v167
	v_lshlrev_b64 v[8:9], 11, v[8:9]
	v_cvt_pk_bf16_f32 v190, v168, v169
	v_cvt_pk_bf16_f32 v191, v170, v171
	v_lshl_add_u64 v[8:9], v[10:11], 0, v[8:9]
	global_store_dwordx4 v[8:9], v[188:191], off
	v_add_u32_e32 v8, s0, v71
	v_ashrrev_i32_e32 v9, 31, v8
	v_cvt_pk_bf16_f32 v192, v172, v173
	v_cvt_pk_bf16_f32 v193, v174, v175
	v_cvt_pk_bf16_f32 v194, v176, v177
	v_lshlrev_b64 v[8:9], 11, v[8:9]
	v_cvt_pk_bf16_f32 v195, v178, v179
	v_lshl_add_u64 v[6:7], v[10:11], 0, v[8:9]
	global_store_dwordx4 v[6:7], v[192:195], off
	s_waitcnt lgkmcnt(0)
